# combo6
# speedup vs baseline: 1.0051x; 1.0051x over previous
.LBB0_928:
	s_or_saveexec_b64 s[20:21], s[20:21]
	s_lshl_b32 s23, s23, 6
	s_and_b32 s23, s23, 0x3c0
	v_mov_b32_e32 v2, 0
	v_mov_b32_e32 v3, 0
	v_mov_b32_e32 v4, 0
	v_mov_b32_e32 v5, 0
	v_mov_b32_e32 v6, 0
	v_mov_b32_e32 v7, 0
	v_mov_b32_e32 v8, 0
	v_mov_b32_e32 v9, 0
	s_xor_b64 exec, exec, s[20:21]
	s_cbranch_execz .LBB0_895
	s_movk_i32 s24, 0x97f
	v_add_u32_e32 v2, 0xffffffa0, v29
	v_cmp_lt_i32_e32 vcc, s24, v29
	s_nop 1
	v_cndmask_b32_e32 v2, v29, v2, vcc
	v_cndmask_b32_e64 v2, v2, v29, s[12:13]
	v_add_u32_e32 v29, s23, v22
	v_mad_i64_i32 v[4:5], s[12:13], s18, v29, 0
	v_ashrrev_i32_e32 v3, 31, v2
	v_lshl_add_u64 v[4:5], v[4:5], 2, s[16:17]
	v_lshlrev_b64 v[6:7], 2, v[2:3]
	v_lshl_add_u64 v[2:3], v[4:5], 0, v[6:7]
	v_add_u32_e32 v4, 16, v29
	v_mad_i64_i32 v[4:5], s[12:13], s18, v4, 0
	v_lshl_add_u64 v[4:5], v[4:5], 2, s[16:17]
	v_lshl_add_u64 v[8:9], v[4:5], 0, v[6:7]
	global_load_dwordx4 v[48:51], v[2:3], off
	global_load_dwordx4 v[52:55], v[8:9], off
	v_add_u32_e32 v56, 32, v29
	v_mad_i64_i32 v[2:3], s[12:13], s18, v56, 0
	v_add_u32_e32 v56, 48, v29
	v_mad_i64_i32 v[8:9], s[12:13], s18, v56, 0
	v_lshl_add_u64 v[2:3], v[2:3], 2, s[16:17]
	v_lshl_add_u64 v[8:9], v[8:9], 2, s[16:17]
	v_lshl_add_u64 v[2:3], v[2:3], 0, v[6:7]
	v_lshl_add_u64 v[6:7], v[8:9], 0, v[6:7]
	global_load_dwordx4 v[2:5], v[2:3], off
	s_nop 0
	global_load_dwordx4 v[6:9], v[6:7], off
	s_waitcnt vmcnt(3)
	ds_write2_b32 v28, v48, v49 offset1:1
	ds_write2_b32 v28, v50, v51 offset0:2 offset1:3
	s_waitcnt vmcnt(2)
	ds_write2_b32 v0, v52, v53 offset1:1
	ds_write2_b32 v17, v54, v55 offset1:1
	s_branch .LBB0_895
